# speedup vs baseline: 1.0361x; 1.0005x over previous
; DEVI void partialSM(f32x16& p0, f32x16& p1, float& m_reg, float& mn, float& alpha) {
;   constexpr float C = SCALE * 1.4426950408889634f;
;   float pmax = p0[0];
; #pragma unroll
;   for (int r = 1; r < 16; ++r) pmax = fmaxf(pmax, p0[r]);
; #pragma unroll
;   for (int r = 0; r < 16; ++r) pmax = fmaxf(pmax, p1[r]);
;   { auto rr = __builtin_amdgcn_permlane32_swap(__float_as_uint(pmax), __float_as_uint(pmax), false, false);
; template <int D0> DEVI void pv_one(f32x16& od, int vb, bf16x8 pa0, bf16x8 pa1, bf16x8 pa2, bf16x8 pa3) {
;   const s16x4 l0 = tr_read<v_rd_off(D0, 0, 0)>(vb), h0 = tr_read<v_rd_off(D0, 0, 1)>(vb), l1 = tr_read<v_rd_off(D0, 1, 0)>(vb), h1 = tr_read<v_rd_off(D0, 1, 1)>(vb);
;   const s16x4 l2 = tr_read<v_rd_off(D0, 2, 0)>(vb), h2 = tr_read<v_rd_off(D0, 2, 1)>(vb), l3 = tr_read<v_rd_off(D0, 3, 0)>(vb), h3 = tr_read<v_rd_off(D0, 3, 1)>(vb);
;   asm volatile("s_waitcnt lgkmcnt(0)" ::: "memory"); SBAR();
;     ...
;   od = __builtin_amdgcn_mfma_f32_32x32x16_bf16(pa0, PK(l0, h0), od, 0, 0, 0);
;   od = __builtin_amdgcn_mfma_f32_32x32x16_bf16(pa1, PK(l1, h1), od, 0, 0, 0);
;   od = __builtin_amdgcn_mfma_f32_32x32x16_bf16(pa2, PK(l2, h2), od, 0, 0, 0);
;   od = __builtin_amdgcn_mfma_f32_32x32x16_bf16(pa3, PK(l3, h3), od, 0, 0, 0);
;     ...
; }
; DEVI void pv_d0(f32x16* o, int vb, bf16x8 pa0, bf16x8 pa1, bf16x8 pa2, bf16x8 pa3) {
;   pv_one<0>(o[0], vb, pa0, pa1, pa2, pa3); pv_one<1>(o[1], vb, pa0, pa1, pa2, pa3); pv_one<2>(o[2], vb, pa0, pa1, pa2, pa3); pv_one<3>(o[3], vb, pa0, pa1, pa2, pa3);
; }
; DEVI void body(const bf16_t* __restrict__ Qb, const bf16_t* __restrict__ Kh, const bf16_t* __restrict__ Vh, bf16_t* __restrict__ Ob, int seq, char* lds) {
;   const int tid = ltid(), wid = tid >> 6, lane = tid & 63, r32 = lane & 31, hi = lane >> 5;
;   char* V_lds = lds; char* K_lds = lds + 2 * SHM_V;
;   float* ws = (float*)(lds + 2 * SHM_V + 2 * SHM_K) + wid * 64; float* li_l = ws; float* al_l = ws + 32;
;   float m_reg = -1e30f, l_reg = 0; f32x16 o[4] = {}; bf16x8 qr[8];
;   const bf16_t* Qw = Qb + (long)(wid * QBLK + r32) * LDQ + hi * 8;
; #pragma unroll
;   for (int d0 = 0; d0 < 8; ++d0) qr[d0] = *reinterpret_cast<const bf16x8*>(Qw + d0 * 16);
;   const int sr = tid >> 4, sc = (tid & 15) * 8, vst0 = v_st(sr, sc), vst1 = v_st(32 + sr, sc);
;   const int vb0 = (int)(uintptr_t)V_lds + v_rd_base(lane);
;   struct { bf16x8 vs0, vs1, ks0, ks1; } sr_[2];
.LBB0_2674:
	ds_read_b64_tr_b16 v[212:213], v190 offset:0
	ds_read_b64_tr_b16 v[214:215], v190 offset:0x800
	ds_read_b64_tr_b16 v[240:241], v190 offset:0x1000
	ds_read_b64_tr_b16 v[242:243], v190 offset:0x1800
	ds_read_b64_tr_b16 v[244:245], v190 offset:0x2000
	ds_read_b64_tr_b16 v[246:247], v190 offset:0x2800
	ds_read_b64_tr_b16 v[248:249], v190 offset:0x3000
	ds_read_b64_tr_b16 v[250:251], v190 offset:0x3800
	s_waitcnt lgkmcnt(6)
	s_nop 0
	v_mfma_f32_32x32x16_bf16 v[50:65], v[162:165], v[212:215], v[50:65]
	ds_read_b64_tr_b16 v[212:213], v190 offset:0x200
	ds_read_b64_tr_b16 v[214:215], v190 offset:0xa00
	s_waitcnt lgkmcnt(6)
	v_mfma_f32_32x32x16_bf16 v[50:65], v[166:169], v[240:243], v[50:65]
	ds_read_b64_tr_b16 v[240:241], v190 offset:0x1200
	ds_read_b64_tr_b16 v[242:243], v190 offset:0x1a00
	s_waitcnt lgkmcnt(6)
	v_mfma_f32_32x32x16_bf16 v[50:65], v[170:173], v[244:247], v[50:65]
	ds_read_b64_tr_b16 v[244:245], v190 offset:0x2200
	ds_read_b64_tr_b16 v[246:247], v190 offset:0x2a00
	s_waitcnt lgkmcnt(6)
	v_mfma_f32_32x32x16_bf16 v[50:65], v[174:177], v[248:251], v[50:65]
	ds_read_b64_tr_b16 v[248:249], v190 offset:0x3200
	ds_read_b64_tr_b16 v[250:251], v190 offset:0x3a00
	s_waitcnt lgkmcnt(6)
	v_mfma_f32_32x32x16_bf16 v[34:49], v[162:165], v[212:215], v[34:49]
	ds_read_b64_tr_b16 v[212:213], v190 offset:0x400
	ds_read_b64_tr_b16 v[214:215], v190 offset:0xc00
	s_waitcnt lgkmcnt(6)
	v_mfma_f32_32x32x16_bf16 v[34:49], v[166:169], v[240:243], v[34:49]
	ds_read_b64_tr_b16 v[240:241], v190 offset:0x1400
	ds_read_b64_tr_b16 v[242:243], v190 offset:0x1c00
	s_waitcnt lgkmcnt(6)
	v_mfma_f32_32x32x16_bf16 v[34:49], v[170:173], v[244:247], v[34:49]
	ds_read_b64_tr_b16 v[244:245], v190 offset:0x2400
	ds_read_b64_tr_b16 v[246:247], v190 offset:0x2c00
	s_waitcnt lgkmcnt(6)
	v_mfma_f32_32x32x16_bf16 v[34:49], v[174:177], v[248:251], v[34:49]
	ds_read_b64_tr_b16 v[248:249], v190 offset:0x3400
	ds_read_b64_tr_b16 v[250:251], v190 offset:0x3c00
	s_waitcnt lgkmcnt(6)
	v_mfma_f32_32x32x16_bf16 v[18:33], v[162:165], v[212:215], v[18:33]
	ds_read_b64_tr_b16 v[212:213], v190 offset:0x600
	ds_read_b64_tr_b16 v[214:215], v190 offset:0xe00
	s_waitcnt lgkmcnt(6)
	v_mfma_f32_32x32x16_bf16 v[18:33], v[166:169], v[240:243], v[18:33]
	ds_read_b64_tr_b16 v[240:241], v190 offset:0x1600
	ds_read_b64_tr_b16 v[242:243], v190 offset:0x1e00
	s_waitcnt lgkmcnt(6)
	v_mfma_f32_32x32x16_bf16 v[18:33], v[170:173], v[244:247], v[18:33]
	ds_read_b64_tr_b16 v[244:245], v190 offset:0x2600
	ds_read_b64_tr_b16 v[246:247], v190 offset:0x2e00
	s_waitcnt lgkmcnt(6)
	v_mfma_f32_32x32x16_bf16 v[18:33], v[174:177], v[248:251], v[18:33]
	ds_read_b64_tr_b16 v[248:249], v190 offset:0x3600
	ds_read_b64_tr_b16 v[250:251], v190 offset:0x3e00
	s_waitcnt lgkmcnt(6)
	v_mfma_f32_32x32x16_bf16 v[2:17], v[162:165], v[212:215], v[2:17]
	v_max_f32_e32 v162, v83, v83
	v_max_f32_e32 v163, v82, v82
	v_max_f32_e32 v162, v163, v162
	v_max3_f32 v162, v162, v84, v85
	v_max3_f32 v162, v162, v86, v87
	v_max3_f32 v162, v162, v88, v89
	v_max3_f32 v162, v162, v90, v91
	v_max3_f32 v162, v162, v92, v93
	v_max3_f32 v162, v162, v94, v95
	s_waitcnt lgkmcnt(4)
	v_mfma_f32_32x32x16_bf16 v[2:17], v[166:169], v[240:243], v[2:17]
	v_max3_f32 v162, v162, v96, v97
	v_max3_f32 v162, v162, v66, v67
	v_max3_f32 v162, v162, v68, v69
	v_max3_f32 v162, v162, v70, v71
	v_max3_f32 v162, v162, v72, v73
	v_max3_f32 v162, v162, v74, v75
	v_max3_f32 v162, v162, v76, v77
	v_max3_f32 v162, v162, v78, v79
	s_waitcnt lgkmcnt(2)
	v_mfma_f32_32x32x16_bf16 v[2:17], v[170:173], v[244:247], v[2:17]
	v_max3_f32 v162, v162, v80, v81
	v_mov_b32_e32 v163, v162
	s_nop 1
	v_permlane32_swap_b32_e32 v162, v163
	v_max_f32_e32 v163, v163, v163
	v_max_f32_e32 v162, v162, v162
	v_max_f32_e32 v162, v162, v163
	v_sub_f32_e32 v163, v162, v208
	v_cmp_ge_f32_e32 vcc, s1, v163
	v_max_f32_e32 v163, v208, v208
	v_max_f32_e32 v163, v163, v162
	s_waitcnt lgkmcnt(0)
	v_mfma_f32_32x32x16_bf16 v[2:17], v[174:177], v[248:251], v[2:17]
	v_sub_f32_e32 v162, v208, v163
	v_mul_f32_e32 v162, 0x3e0293ee, v162
	v_exp_f32_e32 v162, v162
	s_cmp_eq_u64 vcc, exec
	s_cselect_b64 s[40:41], -1, 0
	s_barrier
	s_waitcnt vmcnt(4)
	v_cndmask_b32_e64 v162, v162, 1.0, s[40:41]
	v_cmp_gt_f32_e32 vcc, 1.0, v162
	s_cmpk_gt_u32 s0, 0x100
	s_cbranch_scc0 .Lattn_nodrain
	s_waitcnt vmcnt(0)
.Lattn_nodrain:
	ds_write_b128 v193, v[146:149] offset:16384
	ds_write_b128 v194, v[150:153] offset:16384
	ds_write_b128 v192, v[154:157] offset:49152
	ds_write_b128 v195, v[158:161] offset:49152
	s_cbranch_vccz .LBB0_2678
	s_and_saveexec_b64 s[16:17], s[38:39]
	ds_write_b32 v188, v162 offset:128
	s_or_b64 exec, exec, s[16:17]
	s_waitcnt lgkmcnt(0)
	v_add_u32_e32 v158, v187, v0
	ds_read_b128 v[146:149], v158 offset:224
	ds_read_b128 v[150:153], v158 offset:192
	ds_read_b128 v[154:157], v158 offset:160
	ds_read_b128 v[158:161], v158 offset:128
	s_waitcnt lgkmcnt(3)
	v_pk_mul_f32 v[62:63], v[62:63], v[146:147]
	s_waitcnt lgkmcnt(2)
	v_pk_mul_f32 v[58:59], v[58:59], v[150:151]
	s_waitcnt lgkmcnt(1)
	v_pk_mul_f32 v[54:55], v[54:55], v[154:155]
	v_pk_mul_f32 v[64:65], v[64:65], v[148:149]
	v_pk_mul_f32 v[60:61], v[60:61], v[152:153]
	v_pk_mul_f32 v[56:57], v[56:57], v[156:157]
	s_waitcnt lgkmcnt(0)
	v_pk_mul_f32 v[52:53], v[52:53], v[160:161]
	v_pk_mul_f32 v[50:51], v[50:51], v[158:159]
	v_pk_mul_f32 v[46:47], v[46:47], v[146:147]
	v_pk_mul_f32 v[42:43], v[42:43], v[150:151]
	v_pk_mul_f32 v[38:39], v[38:39], v[154:155]
	v_pk_mul_f32 v[48:49], v[48:49], v[148:149]
	v_pk_mul_f32 v[44:45], v[44:45], v[152:153]
	v_pk_mul_f32 v[40:41], v[40:41], v[156:157]
	v_pk_mul_f32 v[36:37], v[36:37], v[160:161]
	v_pk_mul_f32 v[34:35], v[34:35], v[158:159]
	v_pk_mul_f32 v[30:31], v[30:31], v[146:147]
	v_pk_mul_f32 v[26:27], v[26:27], v[150:151]
	v_pk_mul_f32 v[22:23], v[22:23], v[154:155]
	v_pk_mul_f32 v[32:33], v[32:33], v[148:149]
	v_pk_mul_f32 v[28:29], v[28:29], v[152:153]
	v_pk_mul_f32 v[24:25], v[24:25], v[156:157]
	v_pk_mul_f32 v[20:21], v[20:21], v[160:161]
	v_pk_mul_f32 v[18:19], v[18:19], v[158:159]
	v_pk_mul_f32 v[14:15], v[14:15], v[146:147]
	v_pk_mul_f32 v[10:11], v[10:11], v[150:151]
	v_pk_mul_f32 v[6:7], v[6:7], v[154:155]
	v_pk_mul_f32 v[16:17], v[16:17], v[148:149]
	v_pk_mul_f32 v[12:13], v[12:13], v[152:153]
	v_pk_mul_f32 v[8:9], v[8:9], v[156:157]
	v_pk_mul_f32 v[4:5], v[4:5], v[160:161]
	v_pk_mul_f32 v[2:3], v[2:3], v[158:159]
